# v031 plus phase 1 SwiGLU epilogue with fewer VALU instructions per row
# baseline (speedup 1.0000x reference)
; __device__ __forceinline__ unsigned cvt_pk_bf16(float lo, float hi) { cvf32x2_t v = {lo, hi}; cvbf16x2_t b = __builtin_convertvector(v, cvbf16x2_t); return __builtin_bit_cast(unsigned, b); }
; __device__ __forceinline__ float fsigm(float x) { return __builtin_amdgcn_rcpf(1.f + __expf(-x)); }
; __device__ __forceinline__ float fsilu(float x) { return x * fsigm(x); }
; __device__ __forceinline__ float row_rs(const float* ssq, int row) { return ssq ? rsqrtf(ssq[row] * (1.f / 1024.f) + RMS_EPS) : 1.f; }
;     __device__ __forceinline__ void operator()(const f32x4 (&acc)[2][2][4][2], const Unit& u, int wr, int wc, int fr, int fq) const {
;         const int row0 = u.pm * BM + wr * 64 + fr, col0 = u.pn * HALF + wc * 32 + 8 * fq;
; #pragma unroll
;         for (int ai = 0; ai < 2; ++ai)
; #pragma unroll
;             for (int m = 0; m < 4; ++m) { const int row = row0 + ai * HALF + m * 16; const float rs = row_rs(ssq, row);
;                 u32x4 w; unsigned pk[4];
; #pragma unroll
;                 for (int n = 0; n < 2; ++n) { const f32x4 g = acc[ai][0][m][n] * rs, up = acc[ai][1][m][n] * rs;
;                     pk[2 * n] = cvt_pk_bf16(fsilu(g[0]) * up[0], fsilu(g[1]) * up[1]); pk[2 * n + 1] = cvt_pk_bf16(fsilu(g[2]) * up[2], fsilu(g[3]) * up[3]); }
;                 w.x = pk[0]; w.y = pk[1]; w.z = pk[2]; w.w = pk[3];
;                 st_wt16(H + (size_t)row * ldh + col0, w); }
.LBB0_148:
	v_mul_f32_e32 v184, 0xbfb8aa3b, v152
	v_mul_f32_e32 v186, v152, v152
	v_mov_b32_e32 v188, 1.0
	v_pk_mul_f32 v[180:181], v[124:125], v[184:185] op_sel_hi:[1,0]
	v_pk_mul_f32 v[182:183], v[126:127], v[184:185] op_sel_hi:[1,0]
	v_pk_mul_f32 v[124:125], v[124:125], v[120:121]
	v_exp_f32_e32 v180, v180
	v_exp_f32_e32 v181, v181
	v_exp_f32_e32 v182, v182
	v_exp_f32_e32 v183, v183
	v_pk_mul_f32 v[126:127], v[126:127], v[122:123]
	v_pk_add_f32 v[180:181], v[180:181], v[188:189] op_sel_hi:[1,0]
	v_pk_add_f32 v[182:183], v[182:183], v[188:189] op_sel_hi:[1,0]
	v_rcp_f32_e32 v180, v180
	v_rcp_f32_e32 v181, v181
	v_rcp_f32_e32 v182, v182
	v_rcp_f32_e32 v183, v183
	v_pk_mul_f32 v[124:125], v[124:125], v[186:187] op_sel_hi:[1,0]
	v_pk_mul_f32 v[126:127], v[126:127], v[186:187] op_sel_hi:[1,0]
	v_pk_mul_f32 v[124:125], v[124:125], v[180:181]
	v_pk_mul_f32 v[126:127], v[126:127], v[182:183]
	v_pk_mul_f32 v[180:181], v[116:117], v[184:185] op_sel_hi:[1,0]
	v_pk_mul_f32 v[182:183], v[118:119], v[184:185] op_sel_hi:[1,0]
	v_pk_mul_f32 v[116:117], v[116:117], v[112:113]
	v_exp_f32_e32 v180, v180
	v_exp_f32_e32 v181, v181
	v_exp_f32_e32 v182, v182
	v_exp_f32_e32 v183, v183
	v_pk_mul_f32 v[118:119], v[118:119], v[114:115]
	v_pk_add_f32 v[180:181], v[180:181], v[188:189] op_sel_hi:[1,0]
	v_pk_add_f32 v[182:183], v[182:183], v[188:189] op_sel_hi:[1,0]
	v_rcp_f32_e32 v180, v180
	v_rcp_f32_e32 v181, v181
	v_rcp_f32_e32 v182, v182
	v_rcp_f32_e32 v183, v183
	v_pk_mul_f32 v[116:117], v[116:117], v[186:187] op_sel_hi:[1,0]
	v_pk_mul_f32 v[118:119], v[118:119], v[186:187] op_sel_hi:[1,0]
	v_pk_mul_f32 v[116:117], v[116:117], v[180:181]
	v_pk_mul_f32 v[118:119], v[118:119], v[182:183]
	v_cvt_pk_bf16_f32 v120, v124, v125
	v_cvt_pk_bf16_f32 v121, v126, v127
	v_cvt_pk_bf16_f32 v122, v116, v117
	v_cvt_pk_bf16_f32 v123, v118, v119
	v_lshl_or_b32 v144, s36, 7, v162
	v_ashrrev_i32_e32 v145, 31, v144
	s_and_b64 vcc, exec, s[6:7]
	v_mov_b64_e32 v[112:113], s[56:57]
	v_mad_i64_i32 v[112:113], s[38:39], v146, s81, v[112:113]
	v_lshl_add_u64 v[112:113], v[144:145], 1, v[112:113]
	s_nop 0
	global_store_dwordx4 v[112:113], v[120:123], off
	s_cbranch_vccnz .LBB0_150
	v_fmamk_f32 v112, v173, 0x3a800000, v166
	v_rsq_f32_e32 v112, v112
	s_nop 0
	v_mov_b32_e32 v150, v112
.LBB0_150:
	v_mul_f32_e32 v184, 0xbfb8aa3b, v150
	v_mul_f32_e32 v186, v150, v150
	v_pk_mul_f32 v[180:181], v[108:109], v[184:185] op_sel_hi:[1,0]
	v_pk_mul_f32 v[182:183], v[110:111], v[184:185] op_sel_hi:[1,0]
	v_pk_mul_f32 v[108:109], v[108:109], v[104:105]
	v_exp_f32_e32 v180, v180
	v_exp_f32_e32 v181, v181
	v_exp_f32_e32 v182, v182
	v_exp_f32_e32 v183, v183
	v_pk_mul_f32 v[110:111], v[110:111], v[106:107]
	v_pk_add_f32 v[180:181], v[180:181], v[188:189] op_sel_hi:[1,0]
	v_pk_add_f32 v[182:183], v[182:183], v[188:189] op_sel_hi:[1,0]
	v_rcp_f32_e32 v180, v180
	v_rcp_f32_e32 v181, v181
	v_rcp_f32_e32 v182, v182
	v_rcp_f32_e32 v183, v183
	v_pk_mul_f32 v[108:109], v[108:109], v[186:187] op_sel_hi:[1,0]
	v_pk_mul_f32 v[110:111], v[110:111], v[186:187] op_sel_hi:[1,0]
	v_pk_mul_f32 v[108:109], v[108:109], v[180:181]
	v_pk_mul_f32 v[110:111], v[110:111], v[182:183]
	v_pk_mul_f32 v[180:181], v[100:101], v[184:185] op_sel_hi:[1,0]
	v_pk_mul_f32 v[182:183], v[102:103], v[184:185] op_sel_hi:[1,0]
	v_pk_mul_f32 v[100:101], v[100:101], v[96:97]
	v_exp_f32_e32 v180, v180
	v_exp_f32_e32 v181, v181
	v_exp_f32_e32 v182, v182
	v_exp_f32_e32 v183, v183
	v_pk_mul_f32 v[102:103], v[102:103], v[98:99]
	v_pk_add_f32 v[180:181], v[180:181], v[188:189] op_sel_hi:[1,0]
	v_pk_add_f32 v[182:183], v[182:183], v[188:189] op_sel_hi:[1,0]
	v_rcp_f32_e32 v180, v180
	v_rcp_f32_e32 v181, v181
	v_rcp_f32_e32 v182, v182
	v_rcp_f32_e32 v183, v183
	v_pk_mul_f32 v[100:101], v[100:101], v[186:187] op_sel_hi:[1,0]
	v_pk_mul_f32 v[102:103], v[102:103], v[186:187] op_sel_hi:[1,0]
	v_pk_mul_f32 v[100:101], v[100:101], v[180:181]
	v_pk_mul_f32 v[102:103], v[102:103], v[182:183]
	v_cvt_pk_bf16_f32 v106, v108, v109
	v_cvt_pk_bf16_f32 v107, v110, v111
	v_cvt_pk_bf16_f32 v108, v100, v101
	v_cvt_pk_bf16_f32 v109, v102, v103
	v_or_b32_e32 v118, 16, v146
	v_mov_b32_e32 v104, 1.0
	s_and_b64 vcc, exec, s[6:7]
	v_mov_b64_e32 v[96:97], s[56:57]
	v_mad_i64_i32 v[96:97], s[38:39], v118, s81, v[96:97]
	v_lshl_add_u64 v[96:97], v[144:145], 1, v[96:97]
	s_nop 0
	global_store_dwordx4 v[96:97], v[106:109], off
	v_mov_b32_e32 v96, 1.0
	s_cbranch_vccnz .LBB0_152
	v_fmamk_f32 v96, v174, 0x3a800000, v166
	v_rsq_f32_e32 v96, v96
	s_nop 0
.LBB0_152:
	v_mul_f32_e32 v184, 0xbfb8aa3b, v96
	v_mul_f32_e32 v186, v96, v96
	v_pk_mul_f32 v[180:181], v[92:93], v[184:185] op_sel_hi:[1,0]
	v_pk_mul_f32 v[182:183], v[94:95], v[184:185] op_sel_hi:[1,0]
	v_pk_mul_f32 v[92:93], v[92:93], v[88:89]
	v_exp_f32_e32 v180, v180
	v_exp_f32_e32 v181, v181
	v_exp_f32_e32 v182, v182
	v_exp_f32_e32 v183, v183
	v_pk_mul_f32 v[94:95], v[94:95], v[90:91]
	v_pk_add_f32 v[180:181], v[180:181], v[188:189] op_sel_hi:[1,0]
	v_pk_add_f32 v[182:183], v[182:183], v[188:189] op_sel_hi:[1,0]
	v_rcp_f32_e32 v180, v180
	v_rcp_f32_e32 v181, v181
	v_rcp_f32_e32 v182, v182
	v_rcp_f32_e32 v183, v183
	v_pk_mul_f32 v[92:93], v[92:93], v[186:187] op_sel_hi:[1,0]
	v_pk_mul_f32 v[94:95], v[94:95], v[186:187] op_sel_hi:[1,0]
	v_pk_mul_f32 v[92:93], v[92:93], v[180:181]
	v_pk_mul_f32 v[94:95], v[94:95], v[182:183]
	v_pk_mul_f32 v[180:181], v[84:85], v[184:185] op_sel_hi:[1,0]
	v_pk_mul_f32 v[182:183], v[86:87], v[184:185] op_sel_hi:[1,0]
	v_pk_mul_f32 v[84:85], v[84:85], v[80:81]
	v_exp_f32_e32 v180, v180
	v_exp_f32_e32 v181, v181
	v_exp_f32_e32 v182, v182
	v_exp_f32_e32 v183, v183
	v_pk_mul_f32 v[86:87], v[86:87], v[82:83]
	v_pk_add_f32 v[180:181], v[180:181], v[188:189] op_sel_hi:[1,0]
	v_pk_add_f32 v[182:183], v[182:183], v[188:189] op_sel_hi:[1,0]
	v_rcp_f32_e32 v180, v180
	v_rcp_f32_e32 v181, v181
	v_rcp_f32_e32 v182, v182
	v_rcp_f32_e32 v183, v183
	v_pk_mul_f32 v[84:85], v[84:85], v[186:187] op_sel_hi:[1,0]
	v_pk_mul_f32 v[86:87], v[86:87], v[186:187] op_sel_hi:[1,0]
	v_pk_mul_f32 v[84:85], v[84:85], v[180:181]
	v_pk_mul_f32 v[86:87], v[86:87], v[182:183]
	v_cvt_pk_bf16_f32 v88, v92, v93
	v_cvt_pk_bf16_f32 v89, v94, v95
	v_cvt_pk_bf16_f32 v90, v84, v85
	v_cvt_pk_bf16_f32 v91, v86, v87
	v_or_b32_e32 v97, 32, v146
	s_and_b64 vcc, exec, s[6:7]
	v_mov_b64_e32 v[80:81], s[56:57]
	v_mad_i64_i32 v[80:81], s[38:39], v97, s81, v[80:81]
	v_lshl_add_u64 v[80:81], v[144:145], 1, v[80:81]
	s_nop 0
	global_store_dwordx4 v[80:81], v[88:91], off
	s_cbranch_vccnz .LBB0_154
	v_fmamk_f32 v80, v175, 0x3a800000, v166
	v_rsq_f32_e32 v80, v80
	s_nop 0
	v_mov_b32_e32 v104, v80
; __device__ __forceinline__ unsigned cvt_pk_bf16(float lo, float hi) { cvf32x2_t v = {lo, hi}; cvbf16x2_t b = __builtin_convertvector(v, cvbf16x2_t); return __builtin_bit_cast(unsigned, b); }
; __device__ __forceinline__ float fsigm(float x) { return __builtin_amdgcn_rcpf(1.f + __expf(-x)); }
; __device__ __forceinline__ float fsilu(float x) { return x * fsigm(x); }
; __device__ __forceinline__ float row_rs(const float* ssq, int row) { return ssq ? rsqrtf(ssq[row] * (1.f / 1024.f) + RMS_EPS) : 1.f; }
;     __device__ __forceinline__ void operator()(const f32x4 (&acc)[2][2][4][2], const Unit& u, int wr, int wc, int fr, int fq) const {
;         const int row0 = u.pm * BM + wr * 64 + fr, col0 = u.pn * HALF + wc * 32 + 8 * fq;
; #pragma unroll
;         for (int ai = 0; ai < 2; ++ai)
; #pragma unroll
;             for (int m = 0; m < 4; ++m) { const int row = row0 + ai * HALF + m * 16; const float rs = row_rs(ssq, row);
;                 u32x4 w; unsigned pk[4];
; #pragma unroll
;                 for (int n = 0; n < 2; ++n) { const f32x4 g = acc[ai][0][m][n] * rs, up = acc[ai][1][m][n] * rs;
;                     pk[2 * n] = cvt_pk_bf16(fsilu(g[0]) * up[0], fsilu(g[1]) * up[1]); pk[2 * n + 1] = cvt_pk_bf16(fsilu(g[2]) * up[2], fsilu(g[3]) * up[3]); }
;                 w.x = pk[0]; w.y = pk[1]; w.z = pk[2]; w.w = pk[3];
;                 st_wt16(H + (size_t)row * ldh + col0, w); }
.LBB0_154:
	v_mul_f32_e32 v184, 0xbfb8aa3b, v104
	v_mul_f32_e32 v186, v104, v104
	v_pk_mul_f32 v[180:181], v[76:77], v[184:185] op_sel_hi:[1,0]
	v_pk_mul_f32 v[182:183], v[78:79], v[184:185] op_sel_hi:[1,0]
	v_pk_mul_f32 v[76:77], v[76:77], v[72:73]
	v_exp_f32_e32 v180, v180
	v_exp_f32_e32 v181, v181
	v_exp_f32_e32 v182, v182
	v_exp_f32_e32 v183, v183
	v_pk_mul_f32 v[78:79], v[78:79], v[74:75]
	v_pk_add_f32 v[180:181], v[180:181], v[188:189] op_sel_hi:[1,0]
	v_pk_add_f32 v[182:183], v[182:183], v[188:189] op_sel_hi:[1,0]
	v_rcp_f32_e32 v180, v180
	v_rcp_f32_e32 v181, v181
	v_rcp_f32_e32 v182, v182
	v_rcp_f32_e32 v183, v183
	v_pk_mul_f32 v[76:77], v[76:77], v[186:187] op_sel_hi:[1,0]
	v_pk_mul_f32 v[78:79], v[78:79], v[186:187] op_sel_hi:[1,0]
	v_pk_mul_f32 v[76:77], v[76:77], v[180:181]
	v_pk_mul_f32 v[78:79], v[78:79], v[182:183]
	v_pk_mul_f32 v[180:181], v[68:69], v[184:185] op_sel_hi:[1,0]
	v_pk_mul_f32 v[182:183], v[70:71], v[184:185] op_sel_hi:[1,0]
	v_pk_mul_f32 v[68:69], v[68:69], v[64:65]
	v_exp_f32_e32 v180, v180
	v_exp_f32_e32 v181, v181
	v_exp_f32_e32 v182, v182
	v_exp_f32_e32 v183, v183
	v_pk_mul_f32 v[70:71], v[70:71], v[66:67]
	v_pk_add_f32 v[180:181], v[180:181], v[188:189] op_sel_hi:[1,0]
	v_pk_add_f32 v[182:183], v[182:183], v[188:189] op_sel_hi:[1,0]
	v_rcp_f32_e32 v180, v180
	v_rcp_f32_e32 v181, v181
	v_rcp_f32_e32 v182, v182
	v_rcp_f32_e32 v183, v183
	v_pk_mul_f32 v[68:69], v[68:69], v[186:187] op_sel_hi:[1,0]
	v_pk_mul_f32 v[70:71], v[70:71], v[186:187] op_sel_hi:[1,0]
	v_pk_mul_f32 v[68:69], v[68:69], v[180:181]
	v_pk_mul_f32 v[70:71], v[70:71], v[182:183]
	v_cvt_pk_bf16_f32 v74, v76, v77
	v_cvt_pk_bf16_f32 v75, v78, v79
	v_cvt_pk_bf16_f32 v76, v68, v69
	v_cvt_pk_bf16_f32 v77, v70, v71
	v_or_b32_e32 v86, 48, v146
	v_mov_b32_e32 v72, 1.0
	s_and_b64 vcc, exec, s[6:7]
	v_mov_b64_e32 v[64:65], s[56:57]
	v_mad_i64_i32 v[64:65], s[38:39], v86, s81, v[64:65]
	v_lshl_add_u64 v[64:65], v[144:145], 1, v[64:65]
	s_nop 0
	global_store_dwordx4 v[64:65], v[74:77], off
	v_mov_b32_e32 v64, 1.0
	s_cbranch_vccnz .LBB0_156
	v_fmamk_f32 v64, v176, 0x3a800000, v166
	v_rsq_f32_e32 v64, v64
	s_nop 0
.LBB0_156:
	v_mul_f32_e32 v184, 0xbfb8aa3b, v64
	v_mul_f32_e32 v186, v64, v64
	v_pk_mul_f32 v[180:181], v[60:61], v[184:185] op_sel_hi:[1,0]
	v_pk_mul_f32 v[182:183], v[62:63], v[184:185] op_sel_hi:[1,0]
	v_pk_mul_f32 v[60:61], v[60:61], v[56:57]
	v_exp_f32_e32 v180, v180
	v_exp_f32_e32 v181, v181
	v_exp_f32_e32 v182, v182
	v_exp_f32_e32 v183, v183
	v_pk_mul_f32 v[62:63], v[62:63], v[58:59]
	v_pk_add_f32 v[180:181], v[180:181], v[188:189] op_sel_hi:[1,0]
	v_pk_add_f32 v[182:183], v[182:183], v[188:189] op_sel_hi:[1,0]
	v_rcp_f32_e32 v180, v180
	v_rcp_f32_e32 v181, v181
	v_rcp_f32_e32 v182, v182
	v_rcp_f32_e32 v183, v183
	v_pk_mul_f32 v[60:61], v[60:61], v[186:187] op_sel_hi:[1,0]
	v_pk_mul_f32 v[62:63], v[62:63], v[186:187] op_sel_hi:[1,0]
	v_pk_mul_f32 v[60:61], v[60:61], v[180:181]
	v_pk_mul_f32 v[62:63], v[62:63], v[182:183]
	v_pk_mul_f32 v[180:181], v[52:53], v[184:185] op_sel_hi:[1,0]
	v_pk_mul_f32 v[182:183], v[54:55], v[184:185] op_sel_hi:[1,0]
	v_pk_mul_f32 v[52:53], v[52:53], v[48:49]
	v_exp_f32_e32 v180, v180
	v_exp_f32_e32 v181, v181
	v_exp_f32_e32 v182, v182
	v_exp_f32_e32 v183, v183
	v_pk_mul_f32 v[54:55], v[54:55], v[50:51]
	v_pk_add_f32 v[180:181], v[180:181], v[188:189] op_sel_hi:[1,0]
	v_pk_add_f32 v[182:183], v[182:183], v[188:189] op_sel_hi:[1,0]
	v_rcp_f32_e32 v180, v180
	v_rcp_f32_e32 v181, v181
	v_rcp_f32_e32 v182, v182
	v_rcp_f32_e32 v183, v183
	v_pk_mul_f32 v[52:53], v[52:53], v[186:187] op_sel_hi:[1,0]
	v_pk_mul_f32 v[54:55], v[54:55], v[186:187] op_sel_hi:[1,0]
	v_pk_mul_f32 v[52:53], v[52:53], v[180:181]
	v_pk_mul_f32 v[54:55], v[54:55], v[182:183]
	v_cvt_pk_bf16_f32 v56, v60, v61
	v_cvt_pk_bf16_f32 v57, v62, v63
	v_cvt_pk_bf16_f32 v58, v52, v53
	v_cvt_pk_bf16_f32 v59, v54, v55
	v_add_u32_e32 v65, 0x80, v146
	s_and_b64 vcc, exec, s[6:7]
	v_mov_b64_e32 v[48:49], s[56:57]
	v_mad_i64_i32 v[48:49], s[38:39], v65, s81, v[48:49]
	v_lshl_add_u64 v[48:49], v[144:145], 1, v[48:49]
	s_nop 0
	global_store_dwordx4 v[48:49], v[56:59], off
	s_cbranch_vccnz .LBB0_158
	v_fmamk_f32 v48, v177, 0x3a800000, v166
	v_rsq_f32_e32 v48, v48
	s_nop 0
	v_mov_b32_e32 v72, v48
; __device__ __forceinline__ unsigned cvt_pk_bf16(float lo, float hi) { cvf32x2_t v = {lo, hi}; cvbf16x2_t b = __builtin_convertvector(v, cvbf16x2_t); return __builtin_bit_cast(unsigned, b); }
; __device__ __forceinline__ float fsigm(float x) { return __builtin_amdgcn_rcpf(1.f + __expf(-x)); }
; __device__ __forceinline__ float fsilu(float x) { return x * fsigm(x); }
; __device__ __forceinline__ float row_rs(const float* ssq, int row) { return ssq ? rsqrtf(ssq[row] * (1.f / 1024.f) + RMS_EPS) : 1.f; }
;     __device__ __forceinline__ void operator()(const f32x4 (&acc)[2][2][4][2], const Unit& u, int wr, int wc, int fr, int fq) const {
;         const int row0 = u.pm * BM + wr * 64 + fr, col0 = u.pn * HALF + wc * 32 + 8 * fq;
; #pragma unroll
;         for (int ai = 0; ai < 2; ++ai)
; #pragma unroll
;             for (int m = 0; m < 4; ++m) { const int row = row0 + ai * HALF + m * 16; const float rs = row_rs(ssq, row);
;                 u32x4 w; unsigned pk[4];
; #pragma unroll
;                 for (int n = 0; n < 2; ++n) { const f32x4 g = acc[ai][0][m][n] * rs, up = acc[ai][1][m][n] * rs;
;                     pk[2 * n] = cvt_pk_bf16(fsilu(g[0]) * up[0], fsilu(g[1]) * up[1]); pk[2 * n + 1] = cvt_pk_bf16(fsilu(g[2]) * up[2], fsilu(g[3]) * up[3]); }
;                 w.x = pk[0]; w.y = pk[1]; w.z = pk[2]; w.w = pk[3];
;                 st_wt16(H + (size_t)row * ldh + col0, w); }
.LBB0_158:
	v_mul_f32_e32 v184, 0xbfb8aa3b, v72
	v_mul_f32_e32 v186, v72, v72
	v_pk_mul_f32 v[180:181], v[44:45], v[184:185] op_sel_hi:[1,0]
	v_pk_mul_f32 v[182:183], v[46:47], v[184:185] op_sel_hi:[1,0]
	v_pk_mul_f32 v[44:45], v[44:45], v[40:41]
	v_exp_f32_e32 v180, v180
	v_exp_f32_e32 v181, v181
	v_exp_f32_e32 v182, v182
	v_exp_f32_e32 v183, v183
	v_pk_mul_f32 v[46:47], v[46:47], v[42:43]
	v_pk_add_f32 v[180:181], v[180:181], v[188:189] op_sel_hi:[1,0]
	v_pk_add_f32 v[182:183], v[182:183], v[188:189] op_sel_hi:[1,0]
	v_rcp_f32_e32 v180, v180
	v_rcp_f32_e32 v181, v181
	v_rcp_f32_e32 v182, v182
	v_rcp_f32_e32 v183, v183
	v_pk_mul_f32 v[44:45], v[44:45], v[186:187] op_sel_hi:[1,0]
	v_pk_mul_f32 v[46:47], v[46:47], v[186:187] op_sel_hi:[1,0]
	v_pk_mul_f32 v[44:45], v[44:45], v[180:181]
	v_pk_mul_f32 v[46:47], v[46:47], v[182:183]
	v_pk_mul_f32 v[180:181], v[36:37], v[184:185] op_sel_hi:[1,0]
	v_pk_mul_f32 v[182:183], v[38:39], v[184:185] op_sel_hi:[1,0]
	v_pk_mul_f32 v[36:37], v[36:37], v[32:33]
	v_exp_f32_e32 v180, v180
	v_exp_f32_e32 v181, v181
	v_exp_f32_e32 v182, v182
	v_exp_f32_e32 v183, v183
	v_pk_mul_f32 v[38:39], v[38:39], v[34:35]
	v_pk_add_f32 v[180:181], v[180:181], v[188:189] op_sel_hi:[1,0]
	v_pk_add_f32 v[182:183], v[182:183], v[188:189] op_sel_hi:[1,0]
	v_rcp_f32_e32 v180, v180
	v_rcp_f32_e32 v181, v181
	v_rcp_f32_e32 v182, v182
	v_rcp_f32_e32 v183, v183
	v_pk_mul_f32 v[36:37], v[36:37], v[186:187] op_sel_hi:[1,0]
	v_pk_mul_f32 v[38:39], v[38:39], v[186:187] op_sel_hi:[1,0]
	v_pk_mul_f32 v[36:37], v[36:37], v[180:181]
	v_pk_mul_f32 v[38:39], v[38:39], v[182:183]
	v_cvt_pk_bf16_f32 v42, v44, v45
	v_cvt_pk_bf16_f32 v43, v46, v47
	v_cvt_pk_bf16_f32 v44, v36, v37
	v_cvt_pk_bf16_f32 v45, v38, v39
	v_add_u32_e32 v54, 0x90, v146
	v_mov_b32_e32 v40, 1.0
	s_and_b64 vcc, exec, s[6:7]
	v_mov_b64_e32 v[32:33], s[56:57]
	v_mad_i64_i32 v[32:33], s[38:39], v54, s81, v[32:33]
	v_lshl_add_u64 v[32:33], v[144:145], 1, v[32:33]
	s_nop 0
	global_store_dwordx4 v[32:33], v[42:45], off
	v_mov_b32_e32 v32, 1.0
	s_cbranch_vccnz .LBB0_160
	v_fmamk_f32 v32, v178, 0x3a800000, v166
	v_rsq_f32_e32 v32, v32
	s_nop 0
.LBB0_160:
	v_mul_f32_e32 v184, 0xbfb8aa3b, v32
	v_mul_f32_e32 v186, v32, v32
	v_pk_mul_f32 v[180:181], v[28:29], v[184:185] op_sel_hi:[1,0]
	v_pk_mul_f32 v[182:183], v[30:31], v[184:185] op_sel_hi:[1,0]
	v_pk_mul_f32 v[28:29], v[28:29], v[24:25]
	v_exp_f32_e32 v180, v180
	v_exp_f32_e32 v181, v181
	v_exp_f32_e32 v182, v182
	v_exp_f32_e32 v183, v183
	v_pk_mul_f32 v[30:31], v[30:31], v[26:27]
	v_pk_add_f32 v[180:181], v[180:181], v[188:189] op_sel_hi:[1,0]
	v_pk_add_f32 v[182:183], v[182:183], v[188:189] op_sel_hi:[1,0]
	v_rcp_f32_e32 v180, v180
	v_rcp_f32_e32 v181, v181
	v_rcp_f32_e32 v182, v182
	v_rcp_f32_e32 v183, v183
	v_pk_mul_f32 v[28:29], v[28:29], v[186:187] op_sel_hi:[1,0]
	v_pk_mul_f32 v[30:31], v[30:31], v[186:187] op_sel_hi:[1,0]
	v_pk_mul_f32 v[28:29], v[28:29], v[180:181]
	v_pk_mul_f32 v[30:31], v[30:31], v[182:183]
	v_pk_mul_f32 v[180:181], v[20:21], v[184:185] op_sel_hi:[1,0]
	v_pk_mul_f32 v[182:183], v[22:23], v[184:185] op_sel_hi:[1,0]
	v_pk_mul_f32 v[20:21], v[20:21], v[16:17]
	v_exp_f32_e32 v180, v180
	v_exp_f32_e32 v181, v181
	v_exp_f32_e32 v182, v182
	v_exp_f32_e32 v183, v183
	v_pk_mul_f32 v[22:23], v[22:23], v[18:19]
	v_pk_add_f32 v[180:181], v[180:181], v[188:189] op_sel_hi:[1,0]
	v_pk_add_f32 v[182:183], v[182:183], v[188:189] op_sel_hi:[1,0]
	v_rcp_f32_e32 v180, v180
	v_rcp_f32_e32 v181, v181
	v_rcp_f32_e32 v182, v182
	v_rcp_f32_e32 v183, v183
	v_pk_mul_f32 v[20:21], v[20:21], v[186:187] op_sel_hi:[1,0]
	v_pk_mul_f32 v[22:23], v[22:23], v[186:187] op_sel_hi:[1,0]
	v_pk_mul_f32 v[20:21], v[20:21], v[180:181]
	v_pk_mul_f32 v[22:23], v[22:23], v[182:183]
	v_cvt_pk_bf16_f32 v24, v28, v29
	v_cvt_pk_bf16_f32 v25, v30, v31
	v_cvt_pk_bf16_f32 v26, v20, v21
	v_cvt_pk_bf16_f32 v27, v22, v23
	v_add_u32_e32 v33, 0xa0, v146
	s_and_b64 vcc, exec, s[6:7]
	v_mov_b64_e32 v[16:17], s[56:57]
	v_mad_i64_i32 v[16:17], s[38:39], v33, s81, v[16:17]
	v_lshl_add_u64 v[16:17], v[144:145], 1, v[16:17]
	s_nop 0
	global_store_dwordx4 v[16:17], v[24:27], off
	s_cbranch_vccnz .LBB0_162
	v_fmamk_f32 v16, v179, 0x3a800000, v166
	v_rsq_f32_e32 v16, v16
	s_nop 0
	v_mov_b32_e32 v40, v16
